# LN pass: latch waits only for next row's loads; software prefetch (touch) of the row two ahead
# speedup vs baseline: 1.0122x; 1.0013x over previous
.Lln_latch_a:
	v_readlane_b32 s0, v253, 2
	v_readlane_b32 s1, v253, 3
	s_and_b64 vcc, exec, s[0:1]
	s_cbranch_vccnz .Lln_wait4
	s_waitcnt vmcnt(2)
	s_branch .LBB0_706
.Lln_latch_b:
	v_readlane_b32 s0, v253, 2
	v_readlane_b32 s1, v253, 3
	s_and_b64 vcc, exec, s[0:1]
	s_cbranch_vccnz .Lln_wait6
.Lln_wait4:
	s_waitcnt vmcnt(4)
	s_branch .LBB0_706
.Lln_wait6:
	s_waitcnt vmcnt(6)
.LBB0_706:
	v_add_co_u32_e32 v224, vcc, 0x80000, v224
	s_nop 1
	v_addc_co_u32_e32 v225, vcc, 0, v225, vcc
	global_load_dword v226, v[224:225], off
	global_load_dword v227, v[224:225], off offset:1024
	v_mov_b64_e32 v[94:95], v[86:87]
	v_mov_b64_e32 v[98:99], v[90:91]
	s_cmp_eq_u32 s29, s24
	v_mov_b64_e32 v[92:93], v[84:85]
	v_mov_b64_e32 v[96:97], v[88:89]
	s_cbranch_scc1 .LBB0_765

.LBB0_719:
	s_cmpk_lt_i32 s16, 0x4000
	s_cselect_b64 s[14:15], -1, 0
	s_ashr_i32 s17, s16, 31
	s_xor_b64 s[34:35], s[8:9], -1
	s_lshl_b64 s[20:21], s[16:17], 11
	s_or_b64 s[14:15], s[34:35], s[14:15]
	s_mov_b64 s[18:19], -1
	s_and_b64 vcc, exec, s[14:15]
	v_lshl_add_u64 v[100:101], v[130:131], 0, s[20:21]
	v_mov_b32_e32 v224, v100
	v_mov_b32_e32 v225, v101
	s_cbranch_vccz .LBB0_721
	global_load_dwordx4 v[84:87], v[100:101], off
	s_mov_b64 s[18:19], 0

.LBB0_725:
	s_cmpk_lt_i32 s0, 0x4000
	s_cselect_b64 s[14:15], -1, 0
	s_and_b64 s[10:11], s[10:11], s[14:15]
	s_and_b64 s[16:17], s[2:3], s[10:11]
	s_mov_b64 s[10:11], -1
	s_and_b64 vcc, exec, s[16:17]
	v_lshlrev_b32_e32 v82, 2, v128
	s_cbranch_vccnz .LBB0_727
	s_add_i32 s10, s0, 0xffffc000
	s_lshr_b32 s10, s10, 3
	s_ashr_i32 s1, s0, 11
	s_add_i32 s16, s10, 8
	s_and_b64 s[10:11], s[14:15], exec
	s_cselect_b32 s1, s1, s16
	v_readlane_b32 s10, v252, 47
	s_add_i32 s1, s1, s10
	s_mul_hi_i32 s11, s1, 9
	s_mul_i32 s1, s1, 9
	v_readlane_b32 s10, v252, 52
	s_add_u32 s10, s1, s10
	s_addc_u32 s11, s11, 0
	s_lshl_b64 s[10:11], s[10:11], 12
	v_readlane_b32 s16, v248, 59
	v_readlane_b32 s17, v248, 60
	s_add_u32 s10, s16, s10
	s_addc_u32 s11, s17, s11
	s_add_u32 s16, s10, 0x1000
	s_addc_u32 s17, s11, 0
	global_load_dwordx4 v[58:61], v126, s[10:11]
	global_load_dwordx4 v[62:65], v126, s[10:11] offset:16
	global_load_dwordx4 v[50:53], v126, s[16:17]
	global_load_dwordx4 v[54:57], v126, s[16:17] offset:16
	global_load_dwordx4 v[74:77], v126, s[10:11] offset:2048
	global_load_dwordx4 v[78:81], v126, s[10:11] offset:2064
	global_load_dwordx4 v[66:69], v82, s[16:17]
	global_load_dwordx4 v[70:73], v82, s[16:17] offset:16
	s_waitcnt vmcnt(0)
	s_mov_b64 s[10:11], s[14:15]

.LBB0_761:
	v_readlane_b32 s0, v253, 4
	v_readlane_b32 s1, v253, 5
	s_andn2_b64 vcc, exec, s[0:1]
	s_cbranch_vccnz .Lln_latch_a
	v_add_f32_e32 v82, 1.0, v50
	v_fma_f32 v82, v82, v96, v58
	v_add_f32_e32 v96, 1.0, v51
	v_fma_f32 v96, v96, v97, v59
	v_add_f32_e32 v97, 1.0, v52
	v_fma_f32 v97, v97, v98, v60
	v_add_f32_e32 v98, 1.0, v53
	v_fma_f32 v98, v98, v99, v61
	v_add_f32_e32 v99, 1.0, v54
	v_fma_f32 v99, v99, v92, v62
	v_add_f32_e32 v92, 1.0, v55
	v_fma_f32 v108, v92, v93, v63
	v_add_f32_e32 v92, 1.0, v56
	v_fma_f32 v109, v92, v94, v64
	v_add_f32_e32 v92, 1.0, v57
	v_fma_f32 v95, v92, v95, v65
	v_cvt_pk_bf16_f32 v92, v82, v96
	v_cvt_pk_bf16_f32 v93, v97, v98
	v_cvt_pk_bf16_f32 v94, v99, v108
	v_cvt_pk_bf16_f32 v95, v109, v95
	v_lshl_add_u64 v[96:97], v[138:139], 0, s[12:13]
	global_store_dwordx4 v[96:97], v[92:95], off
	v_add_f32_e32 v82, 1.0, v66
	v_add_f32_e32 v98, 1.0, v71
	v_add_f32_e32 v92, 1.0, v67
	v_add_f32_e32 v93, 1.0, v68
	v_add_f32_e32 v94, 1.0, v69
	v_add_f32_e32 v95, 1.0, v70
	v_fma_f32 v92, v92, v105, v75
	v_fma_f32 v93, v93, v106, v76
	v_fma_f32 v94, v94, v107, v77
	v_fma_f32 v95, v95, v100, v78
	v_add_f32_e32 v99, 1.0, v72
	v_add_f32_e32 v100, 1.0, v73
	v_fma_f32 v82, v82, v104, v74
	v_fma_f32 v98, v98, v101, v79
	v_fma_f32 v99, v99, v102, v80
	v_fma_f32 v100, v100, v103, v81
	v_cvt_pk_bf16_f32 v92, v82, v92
	v_cvt_pk_bf16_f32 v93, v93, v94
	v_cvt_pk_bf16_f32 v94, v95, v98
	v_cvt_pk_bf16_f32 v95, v99, v100
	global_store_dwordx4 v[96:97], v[92:95], off offset:1024
	s_branch .Lln_latch_b
